# v30 + branch-A pass prologue de-serialised: pass-start barrier no longer drains the Q loads (they overlap the first K/V DMA), first-QK wait no longer drains K1/K2/V0
# speedup vs baseline: 1.0054x; 1.0002x over previous
; __device__ __forceinline__ int v_rd_base(int lane) { return ((lane & 3) << 3) | (((lane >> 2) & 3) << 6) | (((lane >> 4) & 1) << 5) | (((lane >> 5) & 1) << 8); }
; #define DMA_K(T, SL) do { const long t_ = (long)(T) * (KVBLK * LDK); GLDS(ks0 + t_, (lds_uptr)((__attribute__((address_space(3))) char*)kdst + (SL))); \
;     if constexpr (DK == 128) GLDS(ks1 + t_, (lds_uptr)((__attribute__((address_space(3))) char*)kdst + (SL) + 8192)); } while (0)
; #define WBAR(N) asm volatile("s_waitcnt vmcnt(" #N ") lgkmcnt(0)\n\ts_barrier" ::: "memory")
; __device__ __forceinline__ void add_bias(f32x16& p0, f32x16& p1, const float* tb, int relb, int hi) {
;   const float* t = tb + relb + 4 * hi;
; #pragma unroll
;   for (int r = 0; r < 16; ++r) { p0[r] += t[(r & 3) + 8 * (r >> 2)]; p1[r] += t[32 + (r & 3) + 8 * (r >> 2)]; }
; }
; template <int DK, int LDK, bool BIAS, bool NOMAX> ...
;     ...
;   if constexpr (DK == 128) { { const int r = 4 * wid + (lane >> 4), c = (lane & 15) ^ (r & 7); koff0 = r * LDK + c * 8; }
;                              { const int r = 4 * (wid + 8) + (lane >> 4), c = (lane & 15) ^ (r & 7); koff1 = r * LDK + c * 8; } }
;   else { const int r = 8 * wid + (lane >> 3), c = (lane & 7) ^ ((r >> 1) & 7); koff0 = r * LDK + c * 8; }
;   { const int st = 2 * wid + (lane >> 5), kk = (st >> 2) * 8 + ((lane & 31) >> 2), k = (kk & ~0xC) | ((kk & 4) << 1) | ((kk & 8) >> 1); voff0 = k * LDK + (st & 3) * 32 + (lane & 3) * 8; }
;   { const int st = 2 * (wid + 8) + (lane >> 5), kk = (st >> 2) * 8 + ((lane & 31) >> 2), k = (kk & ~0xC) | ((kk & 4) << 1) | ((kk & 8) >> 1); voff1 = k * LDK + (st & 3) * 32 + (lane & 3) * 8; }
;   const bf16_t* ks0 = Kh + koff0; const bf16_t* ks1 = Kh + koff1; const bf16_t* vs0 = Vh + voff0; const bf16_t* vs1 = Vh + voff1;
;   const lds_uptr kdst = (lds_uptr)(K_lds + wid * 1024), vdst = (lds_uptr)(V_lds + wid * 1024);
;     ...
;   float curb = 0.f;
;   f32x16 pA0, pA1, pB0, pB1; float mnA, alA, alB; bf16x8 pa[4]; const int NT = seq / KVBLK;
;   const lds_cptr vp0 = (lds_cptr)V_lds + v_rd_base(lane);
;   const int vb0 = (int)(uintptr_t)V_lds + v_rd_base(lane);
;   WBAR(0);
;   DMA_K(0, 0); DMA_V(0, 0); DMA_K(1, SHM_K); DMA_K(2, 2 * SHM_K);
;   if constexpr (DK == 128) WBAR(6); else WBAR(4);
;   qkt<DK>(pA0, pA1, K_lds, qr, r32, hi);
;   if constexpr (NOMAX) { TBIAS(pA0, pA1, 0); curb = cb_; alA = 1.f;
.LBB0_217:
	s_or_b64 exec, exec, s[12:13]
	s_lshl_b64 s[14:15], s[4:5], 1
	v_mov_b32_e32 v0, v176
	s_add_u32 s16, s80, s14
	s_addc_u32 s17, s81, s15
	v_readfirstlane_b32 s7, v0
	s_ashr_i32 s6, s7, 6
	v_bfe_u32 v41, v0, 3, 3
	v_lshl_or_b32 v2, s6, 3, v41
	v_lshrrev_b32_e32 v3, 1, v2
	s_ashr_i32 s3, s7, 4
	v_xor_b32_e32 v3, v3, v0
	s_and_b32 s18, s3, -16
	s_lshr_b32 s3, s3, 1
	v_and_b32_e32 v40, 31, v0
	v_lshlrev_b32_e32 v3, 3, v3
	s_and_b32 s19, s3, 4
	s_lshl_b32 s3, s6, 2
	v_and_b32_e32 v42, 56, v3
	s_lshl_b32 s2, s6, 1
	v_bfe_u32 v3, v0, 2, 3
	v_bfe_u32 v44, v40, 2, 2
	v_lshrrev_b32_e32 v5, 1, v0
	s_add_i32 s3, s3, 32
	v_bfe_u32 v43, v0, 5, 1
	v_or_b32_e32 v4, s18, v44
	v_and_b32_e32 v45, 8, v5
	v_bitop3_b32 v47, s3, -13, v3 bitop3:0xc8
	s_and_b32 s58, s2, 4
	v_or3_b32 v4, v4, s19, v45
	v_and_or_b32 v5, s2, 2, v43
	v_lshlrev_b32_e32 v22, 3, v0
	v_or3_b32 v3, s58, v47, v45
	v_lshl_or_b32 v2, v2, 10, v42
	v_lshlrev_b32_e32 v4, 10, v4
	v_lshlrev_b32_e32 v5, 5, v5
	v_and_b32_e32 v46, 24, v22
	v_lshlrev_b32_e32 v3, 10, v3
	s_lshl_b32 s2, s6, 10
	v_or3_b32 v4, v4, v5, v46
	v_or3_b32 v6, v3, v5, v46
	v_ashrrev_i32_e32 v3, 31, v2
	s_add_i32 s3, s2, 0
	v_lshl_add_u64 v[36:37], v[2:3], 1, s[16:17]
	v_ashrrev_i32_e32 v5, 31, v4
	s_add_i32 s62, s3, 0x10000
	s_waitcnt lgkmcnt(0)
	s_barrier
	s_mov_b32 m0, s3
	v_lshl_add_u64 v[38:39], v[4:5], 1, s[10:11]
	v_ashrrev_i32_e32 v7, 31, v6
	global_load_lds_dwordx4 v[36:37], off
	s_mov_b32 m0, s62
	v_lshl_add_u64 v[34:35], v[6:7], 1, s[10:11]
	global_load_lds_dwordx4 v[38:39], off
	s_add_i32 m0, s3, 0x12000
	v_lshl_add_u64 v[2:3], v[36:37], 0, s[88:89]
	global_load_lds_dwordx4 v[34:35], off
	s_add_i32 m0, s3, 0x4000
	v_lshlrev_b32_e32 v171, 4, v43
	global_load_lds_dwordx4 v[2:3], off
	v_lshl_add_u64 v[2:3], v[36:37], 0, s[54:55]
	s_add_i32 m0, s3, 0x8000
	v_lshlrev_b32_e32 v190, 7, v40
	global_load_lds_dwordx4 v[2:3], off
	v_add_u32_e32 v49, 0, v190
	v_bitop3_b32 v48, v171, v22, s33 bitop3:0x78
	s_waitcnt vmcnt(4) lgkmcnt(0)
	s_barrier
	v_add_u32_e32 v18, v49, v48
	ds_read_b128 v[2:5], v18
	v_and_b32_e32 v51, 0x70, v22
	v_bitop3_b32 v50, v171, v51, 32 bitop3:0x36
	v_add_u32_e32 v56, v49, v50
	ds_read_b128 v[52:55], v56
	s_waitcnt lgkmcnt(0)
	v_mfma_f32_32x32x16_bf16 v[2:17], v[2:5], v[156:159], 0
	ds_read_b128 v[18:21], v18 offset:4096
	v_bitop3_b32 v206, v171, v51, 64 bitop3:0x36
	v_bitop3_b32 v191, v171, v51, s91 bitop3:0x36
	v_or_b32_e32 v189, v40, v200
	v_mov_b32_e32 v212, v202
	v_mfma_f32_32x32x16_bf16 v[2:17], v[52:55], v[152:155], v[2:17]
	ds_read_b128 v[52:55], v56 offset:4096
	v_add_u32_e32 v56, v49, v206
	s_waitcnt lgkmcnt(1)
	v_mfma_f32_32x32x16_bf16 v[18:33], v[18:21], v[156:159], 0
	s_waitcnt lgkmcnt(0)
	v_mfma_f32_32x32x16_bf16 v[18:33], v[52:55], v[152:155], v[18:33]
	ds_read_b128 v[52:55], v56
	s_waitcnt lgkmcnt(0)
	v_mfma_f32_32x32x16_bf16 v[2:17], v[52:55], v[148:151], v[2:17]
	ds_read_b128 v[52:55], v56 offset:4096
	v_add_u32_e32 v56, v49, v191
	s_waitcnt lgkmcnt(0)
	v_mfma_f32_32x32x16_bf16 v[18:33], v[52:55], v[148:151], v[18:33]
	ds_read_b128 v[52:55], v56
	s_waitcnt lgkmcnt(0)
	v_mfma_f32_32x32x16_bf16 v[2:17], v[52:55], v[144:147], v[2:17]
	ds_read_b128 v[52:55], v56 offset:4096
	s_waitcnt lgkmcnt(0)
	v_mfma_f32_32x32x16_bf16 v[18:33], v[52:55], v[144:147], v[18:33]
	s_and_saveexec_b64 s[4:5], s[42:43]
	s_cbranch_execz .LBB0_219
	v_sub_u32_e32 v52, 0x100, v189
	s_add_i32 s2, 0, 0x1c800
	v_lshlrev_b32_e32 v52, 2, v52
	v_add3_u32 v76, s2, v171, v52
	ds_read2_b32 v[52:53], v76 offset1:1
	ds_read2_b32 v[54:55], v76 offset0:2 offset1:3
	ds_read2_b32 v[56:57], v76 offset0:8 offset1:9
	ds_read2_b32 v[58:59], v76 offset0:10 offset1:11
	ds_read2_b32 v[60:61], v76 offset0:16 offset1:17
	ds_read2_b32 v[62:63], v76 offset0:18 offset1:19
	ds_read2_b32 v[64:65], v76 offset0:24 offset1:25
	ds_read2_b32 v[66:67], v76 offset0:26 offset1:27
	ds_read2_b32 v[68:69], v76 offset0:32 offset1:33
	ds_read2_b32 v[70:71], v76 offset0:34 offset1:35
	ds_read2_b32 v[72:73], v76 offset0:40 offset1:41
	ds_read2_b32 v[74:75], v76 offset0:42 offset1:43
	s_waitcnt lgkmcnt(4)
	v_pk_add_f32 v[16:17], v[16:17], v[66:67]
	v_pk_add_f32 v[14:15], v[14:15], v[64:65]
	v_pk_add_f32 v[12:13], v[12:13], v[62:63]
	v_pk_add_f32 v[10:11], v[10:11], v[60:61]
	ds_read2_b32 v[60:61], v76 offset0:48 offset1:49
	ds_read2_b32 v[62:63], v76 offset0:50 offset1:51
	ds_read2_b32 v[64:65], v76 offset0:56 offset1:57
	ds_read2_b32 v[66:67], v76 offset0:58 offset1:59
	v_pk_add_f32 v[8:9], v[8:9], v[58:59]
	v_pk_add_f32 v[6:7], v[6:7], v[56:57]
	v_pk_add_f32 v[4:5], v[4:5], v[54:55]
	v_pk_add_f32 v[2:3], v[2:3], v[52:53]
	s_waitcnt lgkmcnt(0)
	v_pk_add_f32 v[32:33], v[32:33], v[66:67]
	v_pk_add_f32 v[30:31], v[30:31], v[64:65]
	v_pk_add_f32 v[28:29], v[28:29], v[62:63]
	v_pk_add_f32 v[26:27], v[26:27], v[60:61]
	v_pk_add_f32 v[24:25], v[24:25], v[74:75]
	v_pk_add_f32 v[22:23], v[22:23], v[72:73]
	v_pk_add_f32 v[20:21], v[20:21], v[70:71]
	v_pk_add_f32 v[18:19], v[18:19], v[68:69]
	v_mov_b32_e32 v212, 0

; __device__ __forceinline__ int v_rd_base(int lane) { return ((lane & 3) << 3) | (((lane >> 2) & 3) << 6) | (((lane >> 4) & 1) << 5) | (((lane >> 5) & 1) << 8); }
; #define DMA_K(T, SL) do { const long t_ = (long)(T) * (KVBLK * LDK); GLDS(ks0 + t_, (lds_uptr)((__attribute__((address_space(3))) char*)kdst + (SL))); \
;     if constexpr (DK == 128) GLDS(ks1 + t_, (lds_uptr)((__attribute__((address_space(3))) char*)kdst + (SL) + 8192)); } while (0)
; #define WBAR(N) asm volatile("s_waitcnt vmcnt(" #N ") lgkmcnt(0)\n\ts_barrier" ::: "memory")
; __device__ __forceinline__ void add_bias(f32x16& p0, f32x16& p1, const float* tb, int relb, int hi) {
;   const float* t = tb + relb + 4 * hi;
; #pragma unroll
;   for (int r = 0; r < 16; ++r) { p0[r] += t[(r & 3) + 8 * (r >> 2)]; p1[r] += t[32 + (r & 3) + 8 * (r >> 2)]; }
; }
; template <int DK, int LDK, bool BIAS, bool NOMAX> ...
;     ...
;   if constexpr (DK == 128) { { const int r = 4 * wid + (lane >> 4), c = (lane & 15) ^ (r & 7); koff0 = r * LDK + c * 8; }
;                              { const int r = 4 * (wid + 8) + (lane >> 4), c = (lane & 15) ^ (r & 7); koff1 = r * LDK + c * 8; } }
;   else { const int r = 8 * wid + (lane >> 3), c = (lane & 7) ^ ((r >> 1) & 7); koff0 = r * LDK + c * 8; }
;   { const int st = 2 * wid + (lane >> 5), kk = (st >> 2) * 8 + ((lane & 31) >> 2), k = (kk & ~0xC) | ((kk & 4) << 1) | ((kk & 8) >> 1); voff0 = k * LDK + (st & 3) * 32 + (lane & 3) * 8; }
;   { const int st = 2 * (wid + 8) + (lane >> 5), kk = (st >> 2) * 8 + ((lane & 31) >> 2), k = (kk & ~0xC) | ((kk & 4) << 1) | ((kk & 8) >> 1); voff1 = k * LDK + (st & 3) * 32 + (lane & 3) * 8; }
;   const bf16_t* ks0 = Kh + koff0; const bf16_t* ks1 = Kh + koff1; const bf16_t* vs0 = Vh + voff0; const bf16_t* vs1 = Vh + voff1;
;   const lds_uptr kdst = (lds_uptr)(K_lds + wid * 1024), vdst = (lds_uptr)(V_lds + wid * 1024);
;     ...
;   float curb = 0.f;
;   f32x16 pA0, pA1, pB0, pB1; float mnA, alA, alB; bf16x8 pa[4]; const int NT = seq / KVBLK;
;   const lds_cptr vp0 = (lds_cptr)V_lds + v_rd_base(lane);
;   const int vb0 = (int)(uintptr_t)V_lds + v_rd_base(lane);
;   WBAR(0);
;   DMA_K(0, 0); DMA_V(0, 0); DMA_K(1, SHM_K); DMA_K(2, 2 * SHM_K);
;   if constexpr (DK == 128) WBAR(6); else WBAR(4);
;   qkt<DK>(pA0, pA1, K_lds, qr, r32, hi);
;   if constexpr (NOMAX) { TBIAS(pA0, pA1, 0); curb = cb_; alA = 1.f;
.LBB0_310:
	s_or_b64 exec, exec, s[10:11]
	s_lshl_b64 s[12:13], s[4:5], 1
	v_mov_b32_e32 v0, v176
	s_add_u32 s14, s80, s12
	s_addc_u32 s15, s81, s13
	v_readfirstlane_b32 s17, v0
	s_ashr_i32 s16, s17, 6
	v_bfe_u32 v41, v0, 3, 3
	v_lshl_or_b32 v2, s16, 3, v41
	v_lshrrev_b32_e32 v3, 1, v2
	s_ashr_i32 s3, s17, 4
	v_xor_b32_e32 v3, v3, v0
	s_and_b32 s18, s3, -16
	s_lshr_b32 s3, s3, 1
	v_and_b32_e32 v40, 31, v0
	v_lshlrev_b32_e32 v3, 3, v3
	s_and_b32 s19, s3, 4
	s_lshl_b32 s3, s16, 2
	v_and_b32_e32 v42, 56, v3
	s_lshl_b32 s2, s16, 1
	v_bfe_u32 v3, v0, 2, 3
	v_bfe_u32 v44, v40, 2, 2
	v_lshrrev_b32_e32 v5, 1, v0
	s_add_i32 s3, s3, 32
	v_bfe_u32 v43, v0, 5, 1
	v_or_b32_e32 v4, s18, v44
	v_and_b32_e32 v45, 8, v5
	v_bitop3_b32 v47, s3, -13, v3 bitop3:0xc8
	s_and_b32 s58, s2, 4
	v_or3_b32 v4, v4, s19, v45
	v_and_or_b32 v5, s2, 2, v43
	v_lshlrev_b32_e32 v22, 3, v0
	v_or3_b32 v3, s58, v47, v45
	v_lshl_or_b32 v2, v2, 10, v42
	v_lshlrev_b32_e32 v4, 10, v4
	v_lshlrev_b32_e32 v5, 5, v5
	v_and_b32_e32 v46, 24, v22
	v_lshlrev_b32_e32 v3, 10, v3
	s_lshl_b32 s2, s16, 10
	v_or3_b32 v4, v4, v5, v46
	v_or3_b32 v6, v3, v5, v46
	v_ashrrev_i32_e32 v3, 31, v2
	s_add_i32 s3, s2, 0
	v_lshl_add_u64 v[36:37], v[2:3], 1, s[14:15]
	v_ashrrev_i32_e32 v5, 31, v4
	s_add_i32 s62, s3, 0x10000
	s_waitcnt lgkmcnt(0)
	s_barrier
	s_mov_b32 m0, s3
	v_lshl_add_u64 v[38:39], v[4:5], 1, s[8:9]
	v_ashrrev_i32_e32 v7, 31, v6
	global_load_lds_dwordx4 v[36:37], off
	s_mov_b32 m0, s62
	v_lshl_add_u64 v[34:35], v[6:7], 1, s[8:9]
	global_load_lds_dwordx4 v[38:39], off
	s_add_i32 m0, s3, 0x12000
	v_lshl_add_u64 v[2:3], v[36:37], 0, s[88:89]
	global_load_lds_dwordx4 v[34:35], off
	s_add_i32 m0, s3, 0x4000
	v_lshlrev_b32_e32 v170, 4, v43
	global_load_lds_dwordx4 v[2:3], off
	v_lshl_add_u64 v[2:3], v[36:37], 0, s[54:55]
	s_add_i32 m0, s3, 0x8000
	v_lshlrev_b32_e32 v190, 7, v40
	global_load_lds_dwordx4 v[2:3], off
	v_add_u32_e32 v49, 0, v190
	v_bitop3_b32 v48, v170, v22, s33 bitop3:0x78
	s_waitcnt vmcnt(4) lgkmcnt(0)
	s_barrier
	v_add_u32_e32 v18, v49, v48
	ds_read_b128 v[2:5], v18
	v_and_b32_e32 v51, 0x70, v22
	v_bitop3_b32 v50, v170, v51, 32 bitop3:0x36
	v_add_u32_e32 v56, v49, v50
	ds_read_b128 v[52:55], v56
	s_waitcnt lgkmcnt(0)
	v_mfma_f32_32x32x16_bf16 v[2:17], v[2:5], v[156:159], 0
	ds_read_b128 v[18:21], v18 offset:4096
	v_bitop3_b32 v206, v170, v51, 64 bitop3:0x36
	v_bitop3_b32 v191, v170, v51, s91 bitop3:0x36
	v_or_b32_e32 v189, v40, v200
	v_mov_b32_e32 v212, v202
	v_mfma_f32_32x32x16_bf16 v[2:17], v[52:55], v[152:155], v[2:17]
	ds_read_b128 v[52:55], v56 offset:4096
	v_add_u32_e32 v56, v49, v206
	s_waitcnt lgkmcnt(1)
	v_mfma_f32_32x32x16_bf16 v[18:33], v[18:21], v[156:159], 0
	s_waitcnt lgkmcnt(0)
	v_mfma_f32_32x32x16_bf16 v[18:33], v[52:55], v[152:155], v[18:33]
	ds_read_b128 v[52:55], v56
	s_waitcnt lgkmcnt(0)
	v_mfma_f32_32x32x16_bf16 v[2:17], v[52:55], v[148:151], v[2:17]
	ds_read_b128 v[52:55], v56 offset:4096
	v_add_u32_e32 v56, v49, v191
	s_waitcnt lgkmcnt(0)
	v_mfma_f32_32x32x16_bf16 v[18:33], v[52:55], v[148:151], v[18:33]
	ds_read_b128 v[52:55], v56
	s_waitcnt lgkmcnt(0)
	v_mfma_f32_32x32x16_bf16 v[2:17], v[52:55], v[144:147], v[2:17]
	ds_read_b128 v[52:55], v56 offset:4096
	s_waitcnt lgkmcnt(0)
	v_mfma_f32_32x32x16_bf16 v[18:33], v[52:55], v[144:147], v[18:33]
	s_and_saveexec_b64 s[4:5], s[42:43]
	s_cbranch_execz .LBB0_312
	v_sub_u32_e32 v52, 0x100, v189
	s_add_i32 s2, 0, 0x1c800
	v_lshlrev_b32_e32 v52, 2, v52
	v_add3_u32 v76, s2, v170, v52
	ds_read2_b32 v[52:53], v76 offset1:1
	ds_read2_b32 v[54:55], v76 offset0:2 offset1:3
	ds_read2_b32 v[56:57], v76 offset0:8 offset1:9
	ds_read2_b32 v[58:59], v76 offset0:10 offset1:11
	ds_read2_b32 v[60:61], v76 offset0:16 offset1:17
	ds_read2_b32 v[62:63], v76 offset0:18 offset1:19
	ds_read2_b32 v[64:65], v76 offset0:24 offset1:25
	ds_read2_b32 v[66:67], v76 offset0:26 offset1:27
	ds_read2_b32 v[68:69], v76 offset0:32 offset1:33
	ds_read2_b32 v[70:71], v76 offset0:34 offset1:35
	ds_read2_b32 v[72:73], v76 offset0:40 offset1:41
	ds_read2_b32 v[74:75], v76 offset0:42 offset1:43
	s_waitcnt lgkmcnt(4)
	v_pk_add_f32 v[16:17], v[16:17], v[66:67]
	v_pk_add_f32 v[14:15], v[14:15], v[64:65]
	v_pk_add_f32 v[12:13], v[12:13], v[62:63]
	v_pk_add_f32 v[10:11], v[10:11], v[60:61]
	ds_read2_b32 v[60:61], v76 offset0:48 offset1:49
	ds_read2_b32 v[62:63], v76 offset0:50 offset1:51
	ds_read2_b32 v[64:65], v76 offset0:56 offset1:57
	ds_read2_b32 v[66:67], v76 offset0:58 offset1:59
	v_pk_add_f32 v[8:9], v[8:9], v[58:59]
	v_pk_add_f32 v[6:7], v[6:7], v[56:57]
	v_pk_add_f32 v[4:5], v[4:5], v[54:55]
	v_pk_add_f32 v[2:3], v[2:3], v[52:53]
	s_waitcnt lgkmcnt(0)
	v_pk_add_f32 v[32:33], v[32:33], v[66:67]
	v_pk_add_f32 v[30:31], v[30:31], v[64:65]
	v_pk_add_f32 v[28:29], v[28:29], v[62:63]
	v_pk_add_f32 v[26:27], v[26:27], v[60:61]
	v_pk_add_f32 v[24:25], v[24:25], v[74:75]
	v_pk_add_f32 v[22:23], v[22:23], v[72:73]
	v_pk_add_f32 v[20:21], v[20:21], v[70:71]
	v_pk_add_f32 v[18:19], v[18:19], v[68:69]
	v_mov_b32_e32 v212, 0
